# PEER top-k selection: branch-free rank count + collision check, original branchy code kept as exact-tie fallback
# speedup vs baseline: 1.0179x; 1.0179x over previous
.Lpf_a_slow:
	s_waitcnt lgkmcnt(1)
	ds_read_b128 v[32:35], v136
	v_mov_b32_e32 v45, 1
	v_mov_b32_e32 v46, 1
	s_waitcnt lgkmcnt(0)
	v_cmp_ngt_f32_e32 vcc, v32, v44
	s_and_saveexec_b64 s[0:1], vcc
	s_cbranch_execz .LBB0_1122
	v_cmp_eq_f32_e32 vcc, v32, v44
	v_mov_b32_e32 v46, 0
	s_and_saveexec_b64 s[22:23], vcc
	v_mov_b32_e32 v46, v144
	s_or_b64 exec, exec, s[22:23]

.LBB0_1320:
	s_or_b64 exec, exec, s[0:1]
	s_branch .Lpf_a_rejoin
.Lpf_b_slow:
	s_waitcnt lgkmcnt(1)
	ds_read_b128 v[32:35], v136
	v_mov_b32_e32 v37, 1
	v_mov_b32_e32 v38, 1
	s_waitcnt lgkmcnt(0)
	v_cmp_ngt_f32_e32 vcc, v32, v36
	s_and_saveexec_b64 s[0:1], vcc
	s_cbranch_execz .LBB0_1326
	v_cmp_eq_f32_e32 vcc, v32, v36
	v_mov_b32_e32 v38, 0
	s_and_saveexec_b64 s[22:23], vcc
	v_mov_b32_e32 v38, v144
	s_or_b64 exec, exec, s[22:23]

.LBB0_1118:
	global_load_dword v41, v[38:39], off
	global_load_dword v40, v[36:37], off
	s_waitcnt vmcnt(2)
	v_add_f32_e32 v32, v42, v43
	v_cndmask_b32_e64 v44, v197, v32, s[4:5]
	ds_write_b32 v143, v44
	ds_bpermute_b32 v45, v137, v44
	ds_read_b128 v[46:49], v136
	ds_read_b128 v[50:53], v136 offset:16
	ds_read_b128 v[54:57], v136 offset:32
	ds_read_b128 v[58:61], v136 offset:48
	ds_read_b128 v[62:65], v136 offset:64
	ds_read_b128 v[66:69], v136 offset:80
	ds_read_b128 v[74:77], v136 offset:96
	ds_read_b128 v[78:81], v136 offset:112
	ds_read_b128 v[82:85], v136 offset:128
	ds_read_b128 v[86:89], v136 offset:144
	ds_read_b128 v[90:93], v136 offset:160
	ds_read_b128 v[32:35], v136 offset:176
	v_mov_b32_e32 v70, 0
	v_mov_b32_e32 v71, 0
	v_max_f32_e32 v94, v44, v44
	s_waitcnt lgkmcnt(12)
	v_max_f32_e32 v45, v45, v45
	v_max_f32_e32 v94, v94, v45
	ds_bpermute_b32 v45, v138, v94
	s_waitcnt lgkmcnt(12)
	v_cmp_gt_f32_e64 s[0:1], v46, v44
	v_cmp_gt_f32_e64 s[22:23], v47, v44
	v_cmp_gt_f32_e64 s[98:99], v48, v44
	v_cmp_gt_f32_e64 s[100:101], v49, v44
	v_addc_co_u32_e64 v70, vcc, 0, v70, s[0:1]
	v_addc_co_u32_e64 v71, vcc, 0, v71, s[22:23]
	v_addc_co_u32_e64 v70, vcc, 0, v70, s[98:99]
	v_addc_co_u32_e64 v71, vcc, 0, v71, s[100:101]
	ds_read_b128 v[46:49], v136 offset:192
	s_waitcnt lgkmcnt(12)
	v_cmp_gt_f32_e64 s[0:1], v50, v44
	v_cmp_gt_f32_e64 s[22:23], v51, v44
	v_cmp_gt_f32_e64 s[98:99], v52, v44
	v_cmp_gt_f32_e64 s[100:101], v53, v44
	v_addc_co_u32_e64 v70, vcc, 0, v70, s[0:1]
	v_addc_co_u32_e64 v71, vcc, 0, v71, s[22:23]
	v_addc_co_u32_e64 v70, vcc, 0, v70, s[98:99]
	v_addc_co_u32_e64 v71, vcc, 0, v71, s[100:101]
	s_waitcnt lgkmcnt(11)
	v_cmp_gt_f32_e64 s[0:1], v54, v44
	v_cmp_gt_f32_e64 s[22:23], v55, v44
	v_cmp_gt_f32_e64 s[98:99], v56, v44
	v_cmp_gt_f32_e64 s[100:101], v57, v44
	v_addc_co_u32_e64 v70, vcc, 0, v70, s[0:1]
	v_addc_co_u32_e64 v71, vcc, 0, v71, s[22:23]
	v_addc_co_u32_e64 v70, vcc, 0, v70, s[98:99]
	v_addc_co_u32_e64 v71, vcc, 0, v71, s[100:101]
	s_waitcnt lgkmcnt(10)
	v_cmp_gt_f32_e64 s[0:1], v58, v44
	v_cmp_gt_f32_e64 s[22:23], v59, v44
	v_cmp_gt_f32_e64 s[98:99], v60, v44
	v_cmp_gt_f32_e64 s[100:101], v61, v44
	v_addc_co_u32_e64 v70, vcc, 0, v70, s[0:1]
	v_addc_co_u32_e64 v71, vcc, 0, v71, s[22:23]
	v_addc_co_u32_e64 v70, vcc, 0, v70, s[98:99]
	v_addc_co_u32_e64 v71, vcc, 0, v71, s[100:101]
	s_waitcnt lgkmcnt(1)
	v_max_f32_e32 v45, v45, v45
	v_max_f32_e32 v94, v94, v45
	ds_bpermute_b32 v45, v139, v94
	v_cmp_gt_f32_e64 s[0:1], v62, v44
	v_cmp_gt_f32_e64 s[22:23], v63, v44
	v_cmp_gt_f32_e64 s[98:99], v64, v44
	v_cmp_gt_f32_e64 s[100:101], v65, v44
	v_addc_co_u32_e64 v70, vcc, 0, v70, s[0:1]
	v_addc_co_u32_e64 v71, vcc, 0, v71, s[22:23]
	v_addc_co_u32_e64 v70, vcc, 0, v70, s[98:99]
	v_addc_co_u32_e64 v71, vcc, 0, v71, s[100:101]
	v_cmp_gt_f32_e64 s[0:1], v66, v44
	v_cmp_gt_f32_e64 s[22:23], v67, v44
	v_cmp_gt_f32_e64 s[98:99], v68, v44
	v_cmp_gt_f32_e64 s[100:101], v69, v44
	v_addc_co_u32_e64 v70, vcc, 0, v70, s[0:1]
	v_addc_co_u32_e64 v71, vcc, 0, v71, s[22:23]
	v_addc_co_u32_e64 v70, vcc, 0, v70, s[98:99]
	v_addc_co_u32_e64 v71, vcc, 0, v71, s[100:101]
	v_cmp_gt_f32_e64 s[0:1], v74, v44
	v_cmp_gt_f32_e64 s[22:23], v75, v44
	v_cmp_gt_f32_e64 s[98:99], v76, v44
	v_cmp_gt_f32_e64 s[100:101], v77, v44
	v_addc_co_u32_e64 v70, vcc, 0, v70, s[0:1]
	v_addc_co_u32_e64 v71, vcc, 0, v71, s[22:23]
	v_addc_co_u32_e64 v70, vcc, 0, v70, s[98:99]
	v_addc_co_u32_e64 v71, vcc, 0, v71, s[100:101]
	v_cmp_gt_f32_e64 s[0:1], v78, v44
	v_cmp_gt_f32_e64 s[22:23], v79, v44
	v_cmp_gt_f32_e64 s[98:99], v80, v44
	v_cmp_gt_f32_e64 s[100:101], v81, v44
	v_addc_co_u32_e64 v70, vcc, 0, v70, s[0:1]
	v_addc_co_u32_e64 v71, vcc, 0, v71, s[22:23]
	v_addc_co_u32_e64 v70, vcc, 0, v70, s[98:99]
	v_addc_co_u32_e64 v71, vcc, 0, v71, s[100:101]
	s_waitcnt lgkmcnt(0)
	v_max_f32_e32 v45, v45, v45
	v_max_f32_e32 v94, v94, v45
	ds_bpermute_b32 v45, v140, v94
	v_cmp_gt_f32_e64 s[0:1], v82, v44
	v_cmp_gt_f32_e64 s[22:23], v83, v44
	v_cmp_gt_f32_e64 s[98:99], v84, v44
	v_cmp_gt_f32_e64 s[100:101], v85, v44
	v_addc_co_u32_e64 v70, vcc, 0, v70, s[0:1]
	v_addc_co_u32_e64 v71, vcc, 0, v71, s[22:23]
	v_addc_co_u32_e64 v70, vcc, 0, v70, s[98:99]
	v_addc_co_u32_e64 v71, vcc, 0, v71, s[100:101]
	v_cmp_gt_f32_e64 s[0:1], v86, v44
	v_cmp_gt_f32_e64 s[22:23], v87, v44
	v_cmp_gt_f32_e64 s[98:99], v88, v44
	v_cmp_gt_f32_e64 s[100:101], v89, v44
	v_addc_co_u32_e64 v70, vcc, 0, v70, s[0:1]
	v_addc_co_u32_e64 v71, vcc, 0, v71, s[22:23]
	v_addc_co_u32_e64 v70, vcc, 0, v70, s[98:99]
	v_addc_co_u32_e64 v71, vcc, 0, v71, s[100:101]
	s_waitcnt lgkmcnt(0)
	v_max_f32_e32 v45, v45, v45
	v_max_f32_e32 v94, v94, v45
	ds_bpermute_b32 v45, v141, v94
	v_cmp_gt_f32_e64 s[0:1], v90, v44
	v_cmp_gt_f32_e64 s[22:23], v91, v44
	v_cmp_gt_f32_e64 s[98:99], v92, v44
	v_cmp_gt_f32_e64 s[100:101], v93, v44
	v_addc_co_u32_e64 v70, vcc, 0, v70, s[0:1]
	v_addc_co_u32_e64 v71, vcc, 0, v71, s[22:23]
	v_addc_co_u32_e64 v70, vcc, 0, v70, s[98:99]
	v_addc_co_u32_e64 v71, vcc, 0, v71, s[100:101]
	v_cmp_gt_f32_e64 s[0:1], v32, v44
	v_cmp_gt_f32_e64 s[22:23], v33, v44
	v_cmp_gt_f32_e64 s[98:99], v34, v44
	v_cmp_gt_f32_e64 s[100:101], v35, v44
	v_addc_co_u32_e64 v70, vcc, 0, v70, s[0:1]
	v_addc_co_u32_e64 v71, vcc, 0, v71, s[22:23]
	v_addc_co_u32_e64 v70, vcc, 0, v70, s[98:99]
	v_addc_co_u32_e64 v71, vcc, 0, v71, s[100:101]
	s_waitcnt lgkmcnt(0)
	v_max_f32_e32 v45, v45, v45
	v_max_f32_e32 v94, v94, v45
	ds_bpermute_b32 v45, v142, v94
	v_cmp_gt_f32_e64 s[0:1], v46, v44
	v_cmp_gt_f32_e64 s[22:23], v47, v44
	v_cmp_gt_f32_e64 s[98:99], v48, v44
	v_cmp_gt_f32_e64 s[100:101], v49, v44
	v_addc_co_u32_e64 v70, vcc, 0, v70, s[0:1]
	v_addc_co_u32_e64 v71, vcc, 0, v71, s[22:23]
	v_addc_co_u32_e64 v70, vcc, 0, v70, s[98:99]
	v_addc_co_u32_e64 v71, vcc, 0, v71, s[100:101]
	v_add_u32_e32 v33, v70, v71
	s_waitcnt lgkmcnt(0)
	v_max_f32_e32 v45, v45, v45
	v_max_f32_e32 v32, v94, v45
	v_sub_f32_e32 v32, v44, v32
	v_mul_f32_e32 v32, 0x3fb8aa3b, v32
	v_exp_f32_e32 v32, v32
	v_cmp_gt_i32_e32 vcc, 16, v33
	s_and_b64 vcc, s[4:5], vcc
	s_nop 0
	v_cndmask_b32_e32 v34, 0, v32, vcc
	ds_bpermute_b32 v35, v137, v34
	s_waitcnt lgkmcnt(0)
	v_add_f32_e32 v34, v34, v35
	ds_bpermute_b32 v35, v138, v34
	s_waitcnt lgkmcnt(0)
	v_add_f32_e32 v34, v34, v35
	ds_bpermute_b32 v35, v139, v34
	s_waitcnt lgkmcnt(0)
	v_add_f32_e32 v34, v34, v35
	ds_bpermute_b32 v35, v140, v34
	s_waitcnt lgkmcnt(0)
	v_add_f32_e32 v34, v34, v35
	ds_bpermute_b32 v35, v141, v34
	s_waitcnt lgkmcnt(0)
	v_add_f32_e32 v34, v34, v35
	ds_bpermute_b32 v35, v142, v34
	s_mov_b64 s[22:23], 0
	s_and_saveexec_b64 s[0:1], vcc
	s_cbranch_execz .Lpf_a_skip
	s_waitcnt lgkmcnt(0)
	v_add_f32_e32 v34, v34, v35
	v_lshlrev_b32_e32 v35, 7, v42
	v_and_b32_e32 v51, 0x7f, v43
	v_div_scale_f32 v52, s[22:23], v34, v34, v32
	v_rcp_f32_e32 v53, v52
	v_and_or_b32 v35, v35, s31, v51
	v_add_u32_e32 v33, s24, v33
	v_lshl_add_u32 v33, v33, 2, v136
	v_fma_f32 v51, -v52, v53, 1.0
	v_fmac_f32_e32 v53, v51, v53
	v_div_scale_f32 v51, vcc, v32, v34, v32
	v_mul_f32_e32 v54, v51, v53
	v_fma_f32 v55, -v52, v54, v51
	v_fmac_f32_e32 v54, v55, v53
	v_fma_f32 v51, -v52, v54, v51
	v_div_fmas_f32 v51, v51, v53, v54
	v_div_fixup_f32 v32, v51, v34, v32
	ds_write2st64_b32 v33, v35, v32 offset0:1 offset1:3
	ds_read_b32 v34, v33 offset:256
	s_waitcnt lgkmcnt(0)
	v_cmp_ne_u32_e64 s[22:23], v34, v35
.Lpf_a_skip:
	s_or_b64 exec, exec, s[0:1]
	s_nop 1
	s_cmp_lg_u64 s[22:23], 0
	s_cbranch_scc1 .Lpf_a_slow
.Lpf_a_rejoin:
	s_add_i32 s24, s24, 16
	v_lshl_add_u64 v[36:37], v[36:37], 0, s[20:21]
	s_cmpk_eq_i32 s24, 0x70
	v_lshl_add_u64 v[38:39], v[38:39], 0, s[20:21]
	s_cbranch_scc1 .LBB0_1322
	s_waitcnt vmcnt(1)
	v_mov_b32_e32 v42, v41
	s_waitcnt vmcnt(0)
	v_mov_b32_e32 v43, v40
	s_branch .LBB0_1118
.LBB0_1322:
	s_waitcnt vmcnt(0)
	v_add_f32_e32 v32, v41, v40
	v_cndmask_b32_e64 v36, v197, v32, s[4:5]
	ds_write_b32 v143, v36
	ds_bpermute_b32 v45, v137, v36
	ds_read_b128 v[46:49], v136
	ds_read_b128 v[50:53], v136 offset:16
	ds_read_b128 v[54:57], v136 offset:32
	ds_read_b128 v[58:61], v136 offset:48
	ds_read_b128 v[62:65], v136 offset:64
	ds_read_b128 v[66:69], v136 offset:80
	ds_read_b128 v[74:77], v136 offset:96
	ds_read_b128 v[78:81], v136 offset:112
	ds_read_b128 v[82:85], v136 offset:128
	ds_read_b128 v[86:89], v136 offset:144
	ds_read_b128 v[90:93], v136 offset:160
	ds_read_b128 v[32:35], v136 offset:176
	v_mov_b32_e32 v70, 0
	v_mov_b32_e32 v71, 0
	v_max_f32_e32 v94, v36, v36
	s_waitcnt lgkmcnt(12)
	v_max_f32_e32 v45, v45, v45
	v_max_f32_e32 v94, v94, v45
	ds_bpermute_b32 v45, v138, v94
	s_waitcnt lgkmcnt(12)
	v_cmp_gt_f32_e64 s[0:1], v46, v36
	v_cmp_gt_f32_e64 s[22:23], v47, v36
	v_cmp_gt_f32_e64 s[98:99], v48, v36
	v_cmp_gt_f32_e64 s[100:101], v49, v36
	v_addc_co_u32_e64 v70, vcc, 0, v70, s[0:1]
	v_addc_co_u32_e64 v71, vcc, 0, v71, s[22:23]
	v_addc_co_u32_e64 v70, vcc, 0, v70, s[98:99]
	v_addc_co_u32_e64 v71, vcc, 0, v71, s[100:101]
	ds_read_b128 v[46:49], v136 offset:192
	s_waitcnt lgkmcnt(12)
	v_cmp_gt_f32_e64 s[0:1], v50, v36
	v_cmp_gt_f32_e64 s[22:23], v51, v36
	v_cmp_gt_f32_e64 s[98:99], v52, v36
	v_cmp_gt_f32_e64 s[100:101], v53, v36
	v_addc_co_u32_e64 v70, vcc, 0, v70, s[0:1]
	v_addc_co_u32_e64 v71, vcc, 0, v71, s[22:23]
	v_addc_co_u32_e64 v70, vcc, 0, v70, s[98:99]
	v_addc_co_u32_e64 v71, vcc, 0, v71, s[100:101]
	s_waitcnt lgkmcnt(11)
	v_cmp_gt_f32_e64 s[0:1], v54, v36
	v_cmp_gt_f32_e64 s[22:23], v55, v36
	v_cmp_gt_f32_e64 s[98:99], v56, v36
	v_cmp_gt_f32_e64 s[100:101], v57, v36
	v_addc_co_u32_e64 v70, vcc, 0, v70, s[0:1]
	v_addc_co_u32_e64 v71, vcc, 0, v71, s[22:23]
	v_addc_co_u32_e64 v70, vcc, 0, v70, s[98:99]
	v_addc_co_u32_e64 v71, vcc, 0, v71, s[100:101]
	s_waitcnt lgkmcnt(10)
	v_cmp_gt_f32_e64 s[0:1], v58, v36
	v_cmp_gt_f32_e64 s[22:23], v59, v36
	v_cmp_gt_f32_e64 s[98:99], v60, v36
	v_cmp_gt_f32_e64 s[100:101], v61, v36
	v_addc_co_u32_e64 v70, vcc, 0, v70, s[0:1]
	v_addc_co_u32_e64 v71, vcc, 0, v71, s[22:23]
	v_addc_co_u32_e64 v70, vcc, 0, v70, s[98:99]
	v_addc_co_u32_e64 v71, vcc, 0, v71, s[100:101]
	s_waitcnt lgkmcnt(1)
	v_max_f32_e32 v45, v45, v45
	v_max_f32_e32 v94, v94, v45
	ds_bpermute_b32 v45, v139, v94
	v_cmp_gt_f32_e64 s[0:1], v62, v36
	v_cmp_gt_f32_e64 s[22:23], v63, v36
	v_cmp_gt_f32_e64 s[98:99], v64, v36
	v_cmp_gt_f32_e64 s[100:101], v65, v36
	v_addc_co_u32_e64 v70, vcc, 0, v70, s[0:1]
	v_addc_co_u32_e64 v71, vcc, 0, v71, s[22:23]
	v_addc_co_u32_e64 v70, vcc, 0, v70, s[98:99]
	v_addc_co_u32_e64 v71, vcc, 0, v71, s[100:101]
	v_cmp_gt_f32_e64 s[0:1], v66, v36
	v_cmp_gt_f32_e64 s[22:23], v67, v36
	v_cmp_gt_f32_e64 s[98:99], v68, v36
	v_cmp_gt_f32_e64 s[100:101], v69, v36
	v_addc_co_u32_e64 v70, vcc, 0, v70, s[0:1]
	v_addc_co_u32_e64 v71, vcc, 0, v71, s[22:23]
	v_addc_co_u32_e64 v70, vcc, 0, v70, s[98:99]
	v_addc_co_u32_e64 v71, vcc, 0, v71, s[100:101]
	v_cmp_gt_f32_e64 s[0:1], v74, v36
	v_cmp_gt_f32_e64 s[22:23], v75, v36
	v_cmp_gt_f32_e64 s[98:99], v76, v36
	v_cmp_gt_f32_e64 s[100:101], v77, v36
	v_addc_co_u32_e64 v70, vcc, 0, v70, s[0:1]
	v_addc_co_u32_e64 v71, vcc, 0, v71, s[22:23]
	v_addc_co_u32_e64 v70, vcc, 0, v70, s[98:99]
	v_addc_co_u32_e64 v71, vcc, 0, v71, s[100:101]
	v_cmp_gt_f32_e64 s[0:1], v78, v36
	v_cmp_gt_f32_e64 s[22:23], v79, v36
	v_cmp_gt_f32_e64 s[98:99], v80, v36
	v_cmp_gt_f32_e64 s[100:101], v81, v36
	v_addc_co_u32_e64 v70, vcc, 0, v70, s[0:1]
	v_addc_co_u32_e64 v71, vcc, 0, v71, s[22:23]
	v_addc_co_u32_e64 v70, vcc, 0, v70, s[98:99]
	v_addc_co_u32_e64 v71, vcc, 0, v71, s[100:101]
	s_waitcnt lgkmcnt(0)
	v_max_f32_e32 v45, v45, v45
	v_max_f32_e32 v94, v94, v45
	ds_bpermute_b32 v45, v140, v94
	v_cmp_gt_f32_e64 s[0:1], v82, v36
	v_cmp_gt_f32_e64 s[22:23], v83, v36
	v_cmp_gt_f32_e64 s[98:99], v84, v36
	v_cmp_gt_f32_e64 s[100:101], v85, v36
	v_addc_co_u32_e64 v70, vcc, 0, v70, s[0:1]
	v_addc_co_u32_e64 v71, vcc, 0, v71, s[22:23]
	v_addc_co_u32_e64 v70, vcc, 0, v70, s[98:99]
	v_addc_co_u32_e64 v71, vcc, 0, v71, s[100:101]
	v_cmp_gt_f32_e64 s[0:1], v86, v36
	v_cmp_gt_f32_e64 s[22:23], v87, v36
	v_cmp_gt_f32_e64 s[98:99], v88, v36
	v_cmp_gt_f32_e64 s[100:101], v89, v36
	v_addc_co_u32_e64 v70, vcc, 0, v70, s[0:1]
	v_addc_co_u32_e64 v71, vcc, 0, v71, s[22:23]
	v_addc_co_u32_e64 v70, vcc, 0, v70, s[98:99]
	v_addc_co_u32_e64 v71, vcc, 0, v71, s[100:101]
	s_waitcnt lgkmcnt(0)
	v_max_f32_e32 v45, v45, v45
	v_max_f32_e32 v94, v94, v45
	ds_bpermute_b32 v45, v141, v94
	v_cmp_gt_f32_e64 s[0:1], v90, v36
	v_cmp_gt_f32_e64 s[22:23], v91, v36
	v_cmp_gt_f32_e64 s[98:99], v92, v36
	v_cmp_gt_f32_e64 s[100:101], v93, v36
	v_addc_co_u32_e64 v70, vcc, 0, v70, s[0:1]
	v_addc_co_u32_e64 v71, vcc, 0, v71, s[22:23]
	v_addc_co_u32_e64 v70, vcc, 0, v70, s[98:99]
	v_addc_co_u32_e64 v71, vcc, 0, v71, s[100:101]
	v_cmp_gt_f32_e64 s[0:1], v32, v36
	v_cmp_gt_f32_e64 s[22:23], v33, v36
	v_cmp_gt_f32_e64 s[98:99], v34, v36
	v_cmp_gt_f32_e64 s[100:101], v35, v36
	v_addc_co_u32_e64 v70, vcc, 0, v70, s[0:1]
	v_addc_co_u32_e64 v71, vcc, 0, v71, s[22:23]
	v_addc_co_u32_e64 v70, vcc, 0, v70, s[98:99]
	v_addc_co_u32_e64 v71, vcc, 0, v71, s[100:101]
	s_waitcnt lgkmcnt(0)
	v_max_f32_e32 v45, v45, v45
	v_max_f32_e32 v94, v94, v45
	ds_bpermute_b32 v45, v142, v94
	v_cmp_gt_f32_e64 s[0:1], v46, v36
	v_cmp_gt_f32_e64 s[22:23], v47, v36
	v_cmp_gt_f32_e64 s[98:99], v48, v36
	v_cmp_gt_f32_e64 s[100:101], v49, v36
	v_addc_co_u32_e64 v70, vcc, 0, v70, s[0:1]
	v_addc_co_u32_e64 v71, vcc, 0, v71, s[22:23]
	v_addc_co_u32_e64 v70, vcc, 0, v70, s[98:99]
	v_addc_co_u32_e64 v71, vcc, 0, v71, s[100:101]
	v_add_u32_e32 v33, v70, v71
	s_waitcnt lgkmcnt(0)
	v_max_f32_e32 v45, v45, v45
	v_max_f32_e32 v32, v94, v45
	v_sub_f32_e32 v32, v36, v32
	v_mul_f32_e32 v32, 0x3fb8aa3b, v32
	v_exp_f32_e32 v32, v32
	v_cmp_gt_i32_e32 vcc, 16, v33
	s_and_b64 vcc, s[4:5], vcc
	s_nop 0
	v_cndmask_b32_e32 v34, 0, v32, vcc
	ds_bpermute_b32 v35, v137, v34
	s_waitcnt lgkmcnt(0)
	v_add_f32_e32 v34, v34, v35
	ds_bpermute_b32 v35, v138, v34
	s_waitcnt lgkmcnt(0)
	v_add_f32_e32 v34, v34, v35
	ds_bpermute_b32 v35, v139, v34
	s_waitcnt lgkmcnt(0)
	v_add_f32_e32 v34, v34, v35
	ds_bpermute_b32 v35, v140, v34
	s_waitcnt lgkmcnt(0)
	v_add_f32_e32 v34, v34, v35
	ds_bpermute_b32 v35, v141, v34
	s_waitcnt lgkmcnt(0)
	v_add_f32_e32 v34, v34, v35
	ds_bpermute_b32 v35, v142, v34
	s_mov_b64 s[22:23], 0
	s_and_saveexec_b64 s[0:1], vcc
	s_cbranch_execz .Lpf_b_skip
	s_waitcnt lgkmcnt(0)
	v_add_f32_e32 v34, v34, v35
	v_lshlrev_b32_e32 v35, 7, v41
	v_and_b32_e32 v51, 0x7f, v40
	v_div_scale_f32 v52, s[22:23], v34, v34, v32
	v_rcp_f32_e32 v53, v52
	v_and_or_b32 v35, v35, s31, v51
	v_lshl_add_u32 v33, v33, 2, v136
	v_fma_f32 v51, -v52, v53, 1.0
	v_fmac_f32_e32 v53, v51, v53
	v_div_scale_f32 v51, vcc, v32, v34, v32
	v_mul_f32_e32 v54, v51, v53
	v_fma_f32 v55, -v52, v54, v51
	v_fmac_f32_e32 v54, v55, v53
	v_fma_f32 v51, -v52, v54, v51
	v_div_fmas_f32 v51, v51, v53, v54
	v_div_fixup_f32 v32, v51, v34, v32
	v_add_u32_e32 v33, 0xc0, v33
	ds_write2st64_b32 v33, v35, v32 offset0:2 offset1:4
	ds_read_b32 v34, v33 offset:512
	s_waitcnt lgkmcnt(0)
	v_cmp_ne_u32_e64 s[22:23], v34, v35

.Lpf_b_rejoin:
	ds_read_b128 v[36:39], v136 offset:256
	s_waitcnt lgkmcnt(1)
	ds_read_b128 v[32:35], v136 offset:272
	v_add_f32_e32 v72, v72, v73
	v_fmamk_f32 v72, v72, 0x3a800000, v198
	v_mul_f32_e32 v73, 0x4b800000, v72
	s_waitcnt lgkmcnt(1)
	v_readfirstlane_b32 s0, v36
	s_ashr_i32 s1, s0, 31
	s_lshl_b64 s[0:1], s[0:1], 10
	v_readfirstlane_b32 s22, v37
	v_lshl_add_u64 v[40:41], v[106:107], 0, s[0:1]
	v_readfirstlane_b32 s0, v38
	s_ashr_i32 s23, s22, 31
	s_ashr_i32 s1, s0, 31
	s_lshl_b64 s[22:23], s[22:23], 10
	s_lshl_b64 s[0:1], s[0:1], 10
	v_lshl_add_u64 v[42:43], v[106:107], 0, s[22:23]
	global_load_dwordx4 v[68:71], v[40:41], off
	global_load_dwordx4 v[64:67], v[42:43], off
	v_lshl_add_u64 v[40:41], v[106:107], 0, s[0:1]
	v_readfirstlane_b32 s0, v39
	s_ashr_i32 s1, s0, 31
	s_lshl_b64 s[0:1], s[0:1], 10
	v_lshl_add_u64 v[42:43], v[106:107], 0, s[0:1]
	s_waitcnt lgkmcnt(0)
	v_readfirstlane_b32 s0, v32
	s_ashr_i32 s1, s0, 31
	s_lshl_b64 s[0:1], s[0:1], 10
	global_load_dwordx4 v[60:63], v[40:41], off
	global_load_dwordx4 v[56:59], v[42:43], off
	v_lshl_add_u64 v[40:41], v[106:107], 0, s[0:1]
	v_readfirstlane_b32 s0, v33
	s_ashr_i32 s1, s0, 31
	s_lshl_b64 s[0:1], s[0:1], 10
	v_lshl_add_u64 v[42:43], v[106:107], 0, s[0:1]
	v_readfirstlane_b32 s0, v34
	s_ashr_i32 s1, s0, 31
	s_lshl_b64 s[0:1], s[0:1], 10
	global_load_dwordx4 v[52:55], v[40:41], off
	global_load_dwordx4 v[48:51], v[42:43], off
	v_lshl_add_u64 v[40:41], v[106:107], 0, s[0:1]
	v_readfirstlane_b32 s0, v35
	s_ashr_i32 s1, s0, 31
	s_lshl_b64 s[0:1], s[0:1], 10
	v_lshl_add_u64 v[42:43], v[106:107], 0, s[0:1]
	global_load_dwordx4 v[44:47], v[40:41], off
	s_nop 0
	global_load_dwordx4 v[40:43], v[42:43], off
	v_cmp_gt_f32_e32 vcc, s35, v72
	v_mov_b32_e32 v202, 0
	s_mov_b32 s22, 0
	v_cndmask_b32_e32 v72, v72, v73, vcc
	v_rsq_f32_e32 v72, v72
	v_mov_b32_e32 v204, v196
	v_mov_b32_e32 v203, 0
	s_mov_b32 s23, 0
	v_mul_f32_e32 v73, 0x45800000, v72
	v_cndmask_b32_e32 v72, v72, v73, vcc
	v_mul_f32_e32 v72, 0x3b800000, v72
	v_mul_f32_e32 v73, v12, v72
	v_mul_f32_e32 v126, v28, v73
	v_mul_f32_e32 v28, v8, v72
	v_mul_f32_e32 v124, v24, v28
	v_mul_f32_e32 v24, v4, v72
	v_mul_f32_e32 v122, v20, v24
	v_mul_f32_e32 v20, v0, v72
	v_mul_f32_e32 v120, v20, v16
	v_mul_f32_e32 v16, v1, v72
	v_mul_f32_e32 v121, v16, v17
	v_mul_f32_e32 v16, v13, v72
	v_mul_f32_e32 v127, v29, v16
	v_pk_mul_f32 v[16:17], v[14:15], v[72:73] op_sel_hi:[1,0]
	v_mul_f32_e32 v20, v3, v72
	v_pk_mul_f32 v[134:135], v[30:31], v[16:17]
	v_mul_f32_e32 v16, v9, v72
	v_mul_f32_e32 v125, v25, v16
	v_pk_mul_f32 v[16:17], v[10:11], v[72:73] op_sel_hi:[1,0]
	v_mul_f32_e32 v129, v20, v19
	v_pk_mul_f32 v[130:131], v[26:27], v[16:17]
	v_mul_f32_e32 v16, v5, v72
	v_mul_f32_e32 v123, v21, v16
	v_pk_mul_f32 v[16:17], v[6:7], v[72:73] op_sel_hi:[1,0]
	s_nop 0
	v_pk_mul_f32 v[132:133], v[22:23], v[16:17]
	v_mul_f32_e32 v16, v2, v72
	v_mul_f32_e32 v128, v16, v18

	.amdhsa_kernel _Z4mega6Params
		.amdhsa_group_segment_fixed_size 66576
		.amdhsa_private_segment_fixed_size 0
		.amdhsa_kernarg_size 696
		.amdhsa_user_sgpr_count 2
		.amdhsa_user_sgpr_dispatch_ptr 0
		.amdhsa_user_sgpr_queue_ptr 0
		.amdhsa_user_sgpr_kernarg_segment_ptr 1
		.amdhsa_user_sgpr_dispatch_id 0
		.amdhsa_user_sgpr_kernarg_preload_length 0
		.amdhsa_user_sgpr_kernarg_preload_offset 0
		.amdhsa_user_sgpr_private_segment_size 0
		.amdhsa_uses_dynamic_stack 0
		.amdhsa_enable_private_segment 0
		.amdhsa_system_sgpr_workgroup_id_x 1
		.amdhsa_system_sgpr_workgroup_id_y 0
		.amdhsa_system_sgpr_workgroup_id_z 0
		.amdhsa_system_sgpr_workgroup_info 0
		.amdhsa_system_vgpr_workitem_id 2
		.amdhsa_next_free_vgpr 244
		.amdhsa_next_free_sgpr 102
		.amdhsa_accum_offset 244
		.amdhsa_reserve_vcc 1
		.amdhsa_float_round_mode_32 0
		.amdhsa_float_round_mode_16_64 0
		.amdhsa_float_denorm_mode_32 3
		.amdhsa_float_denorm_mode_16_64 3
		.amdhsa_dx10_clamp 1
		.amdhsa_ieee_mode 1
		.amdhsa_fp16_overflow 0
		.amdhsa_tg_split 0
		.amdhsa_exception_fp_ieee_invalid_op 0
		.amdhsa_exception_fp_denorm_src 0
		.amdhsa_exception_fp_ieee_div_zero 0
		.amdhsa_exception_fp_ieee_overflow 0
		.amdhsa_exception_fp_ieee_underflow 0
		.amdhsa_exception_fp_ieee_inexact 0
		.amdhsa_exception_int_div_zero 0
	.end_amdhsa_kernel

amdhsa.kernels:
  - .agpr_count:     0
    .args:
      - .offset:         0
        .size:           440
        .value_kind:     by_value
      - .offset:         440
        .size:           4
        .value_kind:     hidden_block_count_x
      - .offset:         444
        .size:           4
        .value_kind:     hidden_block_count_y
      - .offset:         448
        .size:           4
        .value_kind:     hidden_block_count_z
      - .offset:         452
        .size:           2
        .value_kind:     hidden_group_size_x
      - .offset:         454
        .size:           2
        .value_kind:     hidden_group_size_y
      - .offset:         456
        .size:           2
        .value_kind:     hidden_group_size_z
      - .offset:         458
        .size:           2
        .value_kind:     hidden_remainder_x
      - .offset:         460
        .size:           2
        .value_kind:     hidden_remainder_y
      - .offset:         462
        .size:           2
        .value_kind:     hidden_remainder_z
      - .offset:         480
        .size:           8
        .value_kind:     hidden_global_offset_x
      - .offset:         488
        .size:           8
        .value_kind:     hidden_global_offset_y
      - .offset:         496
        .size:           8
        .value_kind:     hidden_global_offset_z
      - .offset:         504
        .size:           2
        .value_kind:     hidden_grid_dims
      - .offset:         528
        .size:           8
        .value_kind:     hidden_multigrid_sync_arg
    .group_segment_fixed_size: 66576
    .kernarg_segment_align: 8
    .kernarg_segment_size: 696
    .language:       OpenCL C
    .language_version:
      - 2
      - 0
    .max_flat_workgroup_size: 256
    .name:           _Z4mega6Params
    .private_segment_fixed_size: 0
    .sgpr_count:     108
    .sgpr_spill_count: 103
    .symbol:         _Z4mega6Params.kd
    .uniform_work_group_size: 1
    .uses_dynamic_stack: false
    .vgpr_count:     244
    .vgpr_spill_count: 0
    .wavefront_size: 64
